# attention serial-section SALU trimming stacked on GEMM barrier hand-off
# speedup vs baseline: 1.0013x; 1.0013x over previous
.LBB0_940:
	s_add_i32 s6, s80, 0xffffe000
	s_and_b32 s6, s6, 0x6000
	s_add_i32 s6, s6, 0
	s_add_i32 s6, s6, 0x14000
	v_add_u32_e32 v3, s6, v206
	v_add_u32_e32 v8, s6, v210
	ds_read_b128 v[4:7], v3
	ds_read_b128 v[8:11], v8 offset:4096
	s_waitcnt lgkmcnt(1)
	v_mfma_f32_32x32x16_bf16 v[132:147], v[4:7], v[176:179], v[82:97]
	v_add_u32_e32 v3, s6, v207
	ds_read_b128 v[12:15], v3
	v_add_u32_e32 v3, s6, v211
	ds_read_b128 v[216:219], v3 offset:4096
	v_add_f32_e32 v3, 0, v100
	v_add_f32_e32 v3, v101, v3
	v_add_f32_e32 v3, v102, v3
	v_add_f32_e32 v3, v103, v3
	v_cvt_pk_bf16_f32 v180, v100, v101
	v_cvt_pk_bf16_f32 v181, v102, v103
	s_waitcnt lgkmcnt(2)
	v_mfma_f32_32x32x16_bf16 v[148:163], v[8:11], v[176:179], v[82:97]
	s_mul_hi_u32 s18, s81, 0xcccccccd
	s_lshr_b32 s18, s18, 2
	s_mul_i32 s18, s18, 0x14000
	v_add_f32_e32 v3, v104, v3
	v_add_f32_e32 v3, v105, v3
	v_add_f32_e32 v3, v106, v3
	v_add_f32_e32 v3, v107, v3
	v_cvt_pk_bf16_f32 v182, v104, v105
	v_cvt_pk_bf16_f32 v183, v106, v107
	s_waitcnt lgkmcnt(1)
	v_mfma_f32_32x32x16_bf16 v[132:147], v[12:15], v[172:175], v[132:147]
	v_add_u32_e32 v4, s6, v208
	v_add_u32_e32 v8, s6, v212
	ds_read_b128 v[4:7], v4
	ds_read_b128 v[220:223], v8 offset:4096
	v_add_f32_e32 v3, v108, v3
	v_add_f32_e32 v3, v109, v3
	v_add_f32_e32 v3, v110, v3
	v_add_f32_e32 v3, v111, v3
	v_cvt_pk_bf16_f32 v12, v108, v109
	v_cvt_pk_bf16_f32 v13, v110, v111
	s_waitcnt lgkmcnt(2)
	v_mfma_f32_32x32x16_bf16 v[148:163], v[216:219], v[172:175], v[148:163]
	v_add_f32_e32 v3, v112, v3
	v_add_f32_e32 v3, v113, v3
	v_add_f32_e32 v3, v114, v3
	v_add_f32_e32 v3, v115, v3
	v_cvt_pk_bf16_f32 v14, v112, v113
	v_cvt_pk_bf16_f32 v15, v114, v115
	s_waitcnt lgkmcnt(1)
	v_mfma_f32_32x32x16_bf16 v[132:147], v[4:7], v[168:171], v[132:147]
	v_add_u32_e32 v8, s6, v209
	v_add_u32_e32 v9, s6, v213
	ds_read_b128 v[216:219], v8
	ds_read_b128 v[224:227], v9 offset:4096
	v_add_f32_e32 v3, v116, v3
	v_add_f32_e32 v3, v117, v3
	v_add_f32_e32 v3, v118, v3
	v_add_f32_e32 v3, v119, v3
	v_cvt_pk_bf16_f32 v8, v116, v117
	v_cvt_pk_bf16_f32 v9, v118, v119
	s_waitcnt lgkmcnt(2)
	v_mfma_f32_32x32x16_bf16 v[148:163], v[220:223], v[168:171], v[148:163]
	v_add_f32_e32 v3, v120, v3
	v_add_f32_e32 v3, v121, v3
	v_add_f32_e32 v3, v122, v3
	v_add_f32_e32 v3, v123, v3
	v_cvt_pk_bf16_f32 v10, v120, v121
	v_cvt_pk_bf16_f32 v11, v122, v123
	s_waitcnt lgkmcnt(1)
	v_mfma_f32_32x32x16_bf16 v[132:147], v[216:219], v[164:167], v[132:147]
	v_add_f32_e32 v3, v124, v3
	v_add_f32_e32 v3, v125, v3
	v_add_f32_e32 v3, v126, v3
	v_add_f32_e32 v3, v127, v3
	v_cvt_pk_bf16_f32 v4, v124, v125
	v_cvt_pk_bf16_f32 v5, v126, v127
	s_waitcnt lgkmcnt(0)
	v_mfma_f32_32x32x16_bf16 v[148:163], v[224:227], v[164:167], v[148:163]
	v_add_f32_e32 v3, v128, v3
	v_add_f32_e32 v3, v129, v3
	v_add_f32_e32 v3, v130, v3
	v_add_f32_e32 v3, v131, v3
	v_cvt_pk_bf16_f32 v6, v128, v129
	v_cvt_pk_bf16_f32 v7, v130, v131
	v_subrev_u32_e32 v243, s18, v215
	ds_read_b64_tr_b16 v[228:229], v243 offset:0
	ds_read_b64_tr_b16 v[230:231], v243 offset:0x800
	ds_read_b64_tr_b16 v[232:233], v243 offset:0x200
	ds_read_b64_tr_b16 v[234:235], v243 offset:0xa00
	ds_read_b64_tr_b16 v[236:237], v243 offset:0x400
	ds_read_b64_tr_b16 v[238:239], v243 offset:0xc00
	ds_read_b64_tr_b16 v[240:241], v243 offset:0x600
	ds_read_b64_tr_b16 v[242:243], v243 offset:0xe00
	s_nop 0
	v_cmp_ge_f32_e32 vcc, s38, v3
	s_cmp_eq_u64 vcc, exec
	s_cbranch_scc0 .LBB0_958

.LBB0_945:
.LBB0_946:
	v_subrev_u32_e32 v16, s18, v215
	ds_read_b64_tr_b16 v[116:117], v16 offset:0x1000
	ds_read_b64_tr_b16 v[118:119], v16 offset:0x1800
	ds_read_b64_tr_b16 v[120:121], v16 offset:0x1200
	ds_read_b64_tr_b16 v[122:123], v16 offset:0x1a00
	ds_read_b64_tr_b16 v[124:125], v16 offset:0x1400
	ds_read_b64_tr_b16 v[126:127], v16 offset:0x1c00
	ds_read_b64_tr_b16 v[128:129], v16 offset:0x1600
	ds_read_b64_tr_b16 v[130:131], v16 offset:0x1e00
	s_waitcnt lgkmcnt(8)
	v_mfma_f32_32x32x16_bf16 v[66:81], v[228:231], v[180:183], v[66:81]
	v_exp_f32_e32 v132, v132
	v_exp_f32_e32 v133, v133
	v_mfma_f32_32x32x16_bf16 v[50:65], v[232:235], v[180:183], v[50:65]
	v_exp_f32_e32 v134, v134
	v_exp_f32_e32 v135, v135
	v_mfma_f32_32x32x16_bf16 v[34:49], v[236:239], v[180:183], v[34:49]
	v_exp_f32_e32 v136, v136
	v_exp_f32_e32 v137, v137
	v_mfma_f32_32x32x16_bf16 v[18:33], v[240:243], v[180:183], v[18:33]
	v_exp_f32_e32 v138, v138
	v_exp_f32_e32 v139, v139
	ds_read_b64_tr_b16 v[100:101], v16 offset:0x2000
	ds_read_b64_tr_b16 v[102:103], v16 offset:0x2800
	ds_read_b64_tr_b16 v[104:105], v16 offset:0x2200
	ds_read_b64_tr_b16 v[106:107], v16 offset:0x2a00
	ds_read_b64_tr_b16 v[108:109], v16 offset:0x2400
	ds_read_b64_tr_b16 v[110:111], v16 offset:0x2c00
	ds_read_b64_tr_b16 v[112:113], v16 offset:0x2600
	ds_read_b64_tr_b16 v[114:115], v16 offset:0x2e00
	s_waitcnt lgkmcnt(8)
	v_mfma_f32_32x32x16_bf16 v[66:81], v[116:119], v[12:15], v[66:81]
	v_exp_f32_e32 v140, v140
	v_exp_f32_e32 v141, v141
	v_mfma_f32_32x32x16_bf16 v[50:65], v[120:123], v[12:15], v[50:65]
	v_exp_f32_e32 v142, v142
	v_exp_f32_e32 v143, v143
	v_mfma_f32_32x32x16_bf16 v[34:49], v[124:127], v[12:15], v[34:49]
	v_exp_f32_e32 v144, v144
	v_exp_f32_e32 v145, v145
	v_mfma_f32_32x32x16_bf16 v[18:33], v[128:131], v[12:15], v[18:33]
	v_exp_f32_e32 v146, v146
	v_exp_f32_e32 v147, v147
	ds_read_b64_tr_b16 v[12:13], v16 offset:0x3000
	ds_read_b64_tr_b16 v[14:15], v16 offset:0x3800
	ds_read_b64_tr_b16 v[116:117], v16 offset:0x3200
	ds_read_b64_tr_b16 v[118:119], v16 offset:0x3a00
	ds_read_b64_tr_b16 v[120:121], v16 offset:0x3400
	ds_read_b64_tr_b16 v[122:123], v16 offset:0x3c00
	ds_read_b64_tr_b16 v[124:125], v16 offset:0x3600
	ds_read_b64_tr_b16 v[126:127], v16 offset:0x3e00
	s_waitcnt lgkmcnt(8)
	v_mfma_f32_32x32x16_bf16 v[66:81], v[100:103], v[8:11], v[66:81]
	v_exp_f32_e32 v148, v148
	v_exp_f32_e32 v149, v149
	v_mfma_f32_32x32x16_bf16 v[50:65], v[104:107], v[8:11], v[50:65]
	v_exp_f32_e32 v150, v150
	v_exp_f32_e32 v151, v151
	v_mfma_f32_32x32x16_bf16 v[34:49], v[108:111], v[8:11], v[34:49]
	v_exp_f32_e32 v152, v152
	v_exp_f32_e32 v153, v153
	v_mfma_f32_32x32x16_bf16 v[18:33], v[112:115], v[8:11], v[18:33]
	v_exp_f32_e32 v154, v154
	v_exp_f32_e32 v155, v155
	s_waitcnt lgkmcnt(0)
	v_mfma_f32_32x32x16_bf16 v[66:81], v[12:15], v[4:7], v[66:81]
	v_exp_f32_e32 v156, v156
	v_exp_f32_e32 v157, v157
	v_mfma_f32_32x32x16_bf16 v[50:65], v[116:119], v[4:7], v[50:65]
	v_exp_f32_e32 v158, v158
	v_exp_f32_e32 v159, v159
	v_mfma_f32_32x32x16_bf16 v[34:49], v[120:123], v[4:7], v[34:49]
	v_exp_f32_e32 v160, v160
	v_exp_f32_e32 v161, v161
	v_mfma_f32_32x32x16_bf16 v[18:33], v[124:127], v[4:7], v[18:33]
	v_exp_f32_e32 v162, v162
	v_exp_f32_e32 v163, v163

.LBB0_950:
	v_add_f32_e32 v16, v3, v184
	s_and_b32 s17, s80, 0x6000
	s_add_i32 s17, s17, 0
	s_add_i32 s17, s17, 0x14000
	v_add_u32_e32 v3, s17, v206
	v_add_u32_e32 v8, s17, v210
	ds_read_b128 v[4:7], v3
	ds_read_b128 v[8:11], v8 offset:4096
	s_waitcnt lgkmcnt(1)
	v_mfma_f32_32x32x16_bf16 v[100:115], v[4:7], v[176:179], v[82:97]
	v_add_u32_e32 v3, s17, v207
	ds_read_b128 v[12:15], v3
	v_add_u32_e32 v3, s17, v211
	ds_read_b128 v[216:219], v3 offset:4096
	v_add_f32_e32 v3, 0, v132
	v_add_f32_e32 v3, v133, v3
	v_add_f32_e32 v3, v134, v3
	v_add_f32_e32 v3, v135, v3
	v_cvt_pk_bf16_f32 v180, v132, v133
	v_cvt_pk_bf16_f32 v181, v134, v135
	s_waitcnt lgkmcnt(2)
	v_mfma_f32_32x32x16_bf16 v[116:131], v[8:11], v[176:179], v[82:97]
	s_mul_hi_u32 s19, s92, 0xcccccccd
	s_lshr_b32 s19, s19, 2
	s_mul_i32 s19, s19, 0x14000
	v_add_f32_e32 v3, v136, v3
	v_add_f32_e32 v3, v137, v3
	v_add_f32_e32 v3, v138, v3
	v_add_f32_e32 v3, v139, v3
	v_cvt_pk_bf16_f32 v182, v136, v137
	v_cvt_pk_bf16_f32 v183, v138, v139
	s_waitcnt lgkmcnt(1)
	v_mfma_f32_32x32x16_bf16 v[100:115], v[12:15], v[172:175], v[100:115]
	v_add_u32_e32 v4, s17, v208
	v_add_u32_e32 v8, s17, v212
	ds_read_b128 v[4:7], v4
	ds_read_b128 v[220:223], v8 offset:4096
	v_add_f32_e32 v3, v140, v3
	v_add_f32_e32 v3, v141, v3
	v_add_f32_e32 v3, v142, v3
	v_add_f32_e32 v3, v143, v3
	v_cvt_pk_bf16_f32 v12, v140, v141
	v_cvt_pk_bf16_f32 v13, v142, v143
	s_waitcnt lgkmcnt(2)
	v_mfma_f32_32x32x16_bf16 v[116:131], v[216:219], v[172:175], v[116:131]
	v_add_f32_e32 v3, v144, v3
	v_add_f32_e32 v3, v145, v3
	v_add_f32_e32 v3, v146, v3
	v_add_f32_e32 v3, v147, v3
	v_cvt_pk_bf16_f32 v14, v144, v145
	v_cvt_pk_bf16_f32 v15, v146, v147
	s_waitcnt lgkmcnt(1)
	v_mfma_f32_32x32x16_bf16 v[100:115], v[4:7], v[168:171], v[100:115]
	v_add_u32_e32 v8, s17, v209
	v_add_u32_e32 v9, s17, v213
	ds_read_b128 v[216:219], v8
	ds_read_b128 v[224:227], v9 offset:4096
	v_add_f32_e32 v3, v148, v3
	v_add_f32_e32 v3, v149, v3
	v_add_f32_e32 v3, v150, v3
	v_add_f32_e32 v3, v151, v3
	v_cvt_pk_bf16_f32 v8, v148, v149
	v_cvt_pk_bf16_f32 v9, v150, v151
	s_waitcnt lgkmcnt(2)
	v_mfma_f32_32x32x16_bf16 v[116:131], v[220:223], v[168:171], v[116:131]
	v_add_f32_e32 v3, v152, v3
	v_add_f32_e32 v3, v153, v3
	v_add_f32_e32 v3, v154, v3
	v_add_f32_e32 v3, v155, v3
	v_cvt_pk_bf16_f32 v10, v152, v153
	v_cvt_pk_bf16_f32 v11, v154, v155
	s_waitcnt lgkmcnt(1)
	v_mfma_f32_32x32x16_bf16 v[100:115], v[216:219], v[164:167], v[100:115]
	v_add_f32_e32 v3, v156, v3
	v_add_f32_e32 v3, v157, v3
	v_add_f32_e32 v3, v158, v3
	v_add_f32_e32 v3, v159, v3
	v_cvt_pk_bf16_f32 v4, v156, v157
	v_cvt_pk_bf16_f32 v5, v158, v159
	s_waitcnt lgkmcnt(0)
	v_mfma_f32_32x32x16_bf16 v[116:131], v[224:227], v[164:167], v[116:131]
	v_add_f32_e32 v3, v160, v3
	v_add_f32_e32 v3, v161, v3
	v_add_f32_e32 v3, v162, v3
	v_add_f32_e32 v17, v163, v3
	v_cvt_pk_bf16_f32 v6, v160, v161
	v_cvt_pk_bf16_f32 v7, v162, v163
	v_subrev_u32_e32 v243, s19, v214
	ds_read_b64_tr_b16 v[228:229], v243 offset:0
	ds_read_b64_tr_b16 v[230:231], v243 offset:0x800
	ds_read_b64_tr_b16 v[232:233], v243 offset:0x200
	ds_read_b64_tr_b16 v[234:235], v243 offset:0xa00
	ds_read_b64_tr_b16 v[236:237], v243 offset:0x400
	ds_read_b64_tr_b16 v[238:239], v243 offset:0xc00
	ds_read_b64_tr_b16 v[240:241], v243 offset:0x600
	ds_read_b64_tr_b16 v[242:243], v243 offset:0xe00
	s_nop 0
	v_cmp_ge_f32_e32 vcc, s38, v17
	s_cmp_eq_u64 vcc, exec
	s_cbranch_scc0 .LBB0_960

.LBB0_955:
.LBB0_956:
	v_pk_add_f32 v[184:185], v[16:17], v[16:17] op_sel:[1,0] op_sel_hi:[0,1]
	v_subrev_u32_e32 v3, s19, v214
	ds_read_b64_tr_b16 v[148:149], v3 offset:0x1000
	ds_read_b64_tr_b16 v[150:151], v3 offset:0x1800
	ds_read_b64_tr_b16 v[152:153], v3 offset:0x1200
	ds_read_b64_tr_b16 v[154:155], v3 offset:0x1a00
	ds_read_b64_tr_b16 v[156:157], v3 offset:0x1400
	ds_read_b64_tr_b16 v[158:159], v3 offset:0x1c00
	ds_read_b64_tr_b16 v[160:161], v3 offset:0x1600
	ds_read_b64_tr_b16 v[162:163], v3 offset:0x1e00
	s_waitcnt lgkmcnt(8)
	v_mfma_f32_32x32x16_bf16 v[66:81], v[228:231], v[180:183], v[66:81]
	v_exp_f32_e32 v100, v100
	v_exp_f32_e32 v101, v101
	v_mfma_f32_32x32x16_bf16 v[50:65], v[232:235], v[180:183], v[50:65]
	v_exp_f32_e32 v102, v102
	v_exp_f32_e32 v103, v103
	v_mfma_f32_32x32x16_bf16 v[34:49], v[236:239], v[180:183], v[34:49]
	v_exp_f32_e32 v104, v104
	v_exp_f32_e32 v105, v105
	v_mfma_f32_32x32x16_bf16 v[18:33], v[240:243], v[180:183], v[18:33]
	v_exp_f32_e32 v106, v106
	v_exp_f32_e32 v107, v107
	ds_read_b64_tr_b16 v[132:133], v3 offset:0x2000
	ds_read_b64_tr_b16 v[134:135], v3 offset:0x2800
	ds_read_b64_tr_b16 v[136:137], v3 offset:0x2200
	ds_read_b64_tr_b16 v[138:139], v3 offset:0x2a00
	ds_read_b64_tr_b16 v[140:141], v3 offset:0x2400
	ds_read_b64_tr_b16 v[142:143], v3 offset:0x2c00
	ds_read_b64_tr_b16 v[144:145], v3 offset:0x2600
	ds_read_b64_tr_b16 v[146:147], v3 offset:0x2e00
	s_waitcnt lgkmcnt(8)
	v_mfma_f32_32x32x16_bf16 v[66:81], v[148:151], v[12:15], v[66:81]
	v_exp_f32_e32 v108, v108
	v_exp_f32_e32 v109, v109
	v_mfma_f32_32x32x16_bf16 v[50:65], v[152:155], v[12:15], v[50:65]
	v_exp_f32_e32 v110, v110
	v_exp_f32_e32 v111, v111
	v_mfma_f32_32x32x16_bf16 v[34:49], v[156:159], v[12:15], v[34:49]
	v_exp_f32_e32 v112, v112
	v_exp_f32_e32 v113, v113
	v_mfma_f32_32x32x16_bf16 v[18:33], v[160:163], v[12:15], v[18:33]
	v_exp_f32_e32 v114, v114
	v_exp_f32_e32 v115, v115
	ds_read_b64_tr_b16 v[12:13], v3 offset:0x3000
	ds_read_b64_tr_b16 v[14:15], v3 offset:0x3800
	ds_read_b64_tr_b16 v[148:149], v3 offset:0x3200
	ds_read_b64_tr_b16 v[150:151], v3 offset:0x3a00
	ds_read_b64_tr_b16 v[152:153], v3 offset:0x3400
	ds_read_b64_tr_b16 v[154:155], v3 offset:0x3c00
	ds_read_b64_tr_b16 v[156:157], v3 offset:0x3600
	ds_read_b64_tr_b16 v[158:159], v3 offset:0x3e00
	s_waitcnt lgkmcnt(8)
	v_mfma_f32_32x32x16_bf16 v[66:81], v[132:135], v[8:11], v[66:81]
	v_exp_f32_e32 v116, v116
	v_exp_f32_e32 v117, v117
	v_mfma_f32_32x32x16_bf16 v[50:65], v[136:139], v[8:11], v[50:65]
	v_exp_f32_e32 v118, v118
	v_exp_f32_e32 v119, v119
	v_mfma_f32_32x32x16_bf16 v[34:49], v[140:143], v[8:11], v[34:49]
	v_exp_f32_e32 v120, v120
	v_exp_f32_e32 v121, v121
	v_mfma_f32_32x32x16_bf16 v[18:33], v[144:147], v[8:11], v[18:33]
	v_exp_f32_e32 v122, v122
	v_exp_f32_e32 v123, v123
	s_waitcnt lgkmcnt(0)
	v_mfma_f32_32x32x16_bf16 v[66:81], v[12:15], v[4:7], v[66:81]
	v_exp_f32_e32 v124, v124
	v_exp_f32_e32 v125, v125
	v_mfma_f32_32x32x16_bf16 v[50:65], v[148:151], v[4:7], v[50:65]
	v_exp_f32_e32 v126, v126
	v_exp_f32_e32 v127, v127
	v_mfma_f32_32x32x16_bf16 v[34:49], v[152:155], v[4:7], v[34:49]
	v_exp_f32_e32 v128, v128
	v_exp_f32_e32 v129, v129
	v_mfma_f32_32x32x16_bf16 v[18:33], v[156:159], v[4:7], v[18:33]
	v_exp_f32_e32 v130, v130
	v_exp_f32_e32 v131, v131

.LBB0_959:
	s_mov_b32 s30, s16
	s_mov_b32 s31, s16
	s_mov_b32 s17, s16
	s_mov_b32 s18, s16
	s_mov_b32 s19, s16
	s_mov_b32 s20, s16
	s_mov_b32 s21, s16
	s_mov_b32 s22, s16
	s_mov_b32 s23, s16
	s_mov_b32 s24, s16
	s_mov_b32 s25, s16
	s_mov_b32 s26, s16
	s_mov_b32 s27, s16
	s_mov_b32 s28, s16
	s_mov_b32 s29, s16
	v_mov_b64_e32 v[146:147], s[30:31]
	v_mov_b64_e32 v[144:145], s[28:29]
	v_mov_b64_e32 v[142:143], s[26:27]
	v_mov_b64_e32 v[140:141], s[24:25]
	v_mov_b64_e32 v[138:139], s[22:23]
	v_mov_b64_e32 v[136:137], s[20:21]
	v_mov_b64_e32 v[134:135], s[18:19]
	v_mov_b64_e32 v[132:133], s[16:17]
	v_mov_b64_e32 v[162:163], v[146:147]
	v_mov_b64_e32 v[160:161], v[144:145]
	v_mov_b64_e32 v[158:159], v[142:143]
	v_mov_b64_e32 v[156:157], v[140:141]
	v_mov_b64_e32 v[154:155], v[138:139]
	v_mov_b64_e32 v[152:153], v[136:137]
	v_mov_b64_e32 v[150:151], v[134:135]
	v_mov_b64_e32 v[148:149], v[132:133]
	s_mul_hi_u32 s18, s81, 0xcccccccd
	s_lshr_b32 s18, s18, 2
	s_mul_i32 s18, s18, 0x14000
	s_cbranch_execz .LBB0_943
	s_branch .LBB0_946

.LBB0_961:
	s_mov_b32 s30, s16
	s_mov_b32 s31, s16
	s_mov_b32 s17, s16
	s_mov_b32 s18, s16
	s_mov_b32 s19, s16
	s_mov_b32 s20, s16
	s_mov_b32 s21, s16
	s_mov_b32 s22, s16
	s_mov_b32 s23, s16
	s_mov_b32 s24, s16
	s_mov_b32 s25, s16
	s_mov_b32 s26, s16
	s_mov_b32 s27, s16
	s_mov_b32 s28, s16
	s_mov_b32 s29, s16
	v_mov_b64_e32 v[114:115], s[30:31]
	v_mov_b64_e32 v[112:113], s[28:29]
	v_mov_b64_e32 v[110:111], s[26:27]
	v_mov_b64_e32 v[108:109], s[24:25]
	v_mov_b64_e32 v[106:107], s[22:23]
	v_mov_b64_e32 v[104:105], s[20:21]
	v_mov_b64_e32 v[102:103], s[18:19]
	v_mov_b64_e32 v[100:101], s[16:17]
	v_mov_b64_e32 v[130:131], v[114:115]
	v_mov_b64_e32 v[128:129], v[112:113]
	v_mov_b64_e32 v[126:127], v[110:111]
	v_mov_b64_e32 v[124:125], v[108:109]
	v_mov_b64_e32 v[122:123], v[106:107]
	v_mov_b64_e32 v[120:121], v[104:105]
	v_mov_b64_e32 v[118:119], v[102:103]
	v_mov_b64_e32 v[116:117], v[100:101]
	s_mul_hi_u32 s19, s92, 0xcccccccd
	s_lshr_b32 s19, s19, 2
	s_mul_i32 s19, s19, 0x14000
	s_cbranch_execz .LBB0_953
	s_branch .LBB0_956
